# P3 cmp pacing stride 3 (was 4) with dynamic cmp tickets: cmp work is drained before the last rows
# speedup vs baseline: 1.0038x; 1.0038x over previous
; __global__ void __launch_bounds__(NTHR, 2) fwd_kernel(Args a) {
;     ...
;     {
;         const int nrow = (MTOK - gw + NGW - 1) / NGW, ncmp = (8192 - gw + NGW - 1) / NGW;
;         const int stride = nrow > 0 && ncmp > 0 ? (nrow / ncmp > 0 ? nrow / ncmp : 1) : 1, phase = ((wave >> 2) * (stride >> 1) + (wave & 1)) % stride;
;         int ci = 0;
;         for (int i = 0; i < nrow || ci < ncmp; ++i) {
.LBB0_474:
	s_mov_b32 s69, 3
	v_cvt_f32_u32_e32 v1, s69
	s_add_u32 s21, s18, 0x6000000
	s_addc_u32 s68, s19, 0
	s_add_u32 s12, s18, 0x6800000
	v_rcp_iflag_f32_e32 v1, v1
	s_addc_u32 s13, s19, 0
	s_or_b64 s[4:5], s[8:9], s[10:11]
	s_andn2_b64 vcc, exec, s[4:5]
	v_mul_f32_e32 v1, 0x4f7ffffe, v1
	v_cvt_u32_f32_e32 v1, v1
	s_nop 0
	v_readfirstlane_b32 s59, v1
	s_cbranch_vccnz .LBB0_659
	v_lshlrev_b32_e32 v1, 6, v133
	v_or_b32_e32 v37, 47, v1
	v_or_b32_e32 v46, 31, v1
	v_or_b32_e32 v117, 63, v1
	v_add_u32_e32 v119, 0x4f, v1
	v_or_b32_e32 v39, 0xaf, v1
	v_or_b32_e32 v48, 0x9f, v1
	v_or_b32_e32 v202, 0xbf, v1
	v_add_u32_e32 v203, 0xcf, v1
	v_or_b32_e32 v47, 0x12f, v1
	v_or_b32_e32 v50, 0x11f, v1
	v_or_b32_e32 v204, 0x13f, v1
	v_add_u32_e32 v205, 0x14f, v1
	v_or_b32_e32 v49, 0x1af, v1
	v_or_b32_e32 v52, 0x19f, v1
	v_or_b32_e32 v206, 0x1bf, v1
	v_add_u32_e32 v207, 0x1cf, v1
	v_or_b32_e32 v51, 0x22f, v1
	v_or_b32_e32 v54, 0x21f, v1
	v_or_b32_e32 v208, 0x23f, v1
	v_add_u32_e32 v209, 0x24f, v1
	v_or_b32_e32 v53, 0x2af, v1
	v_or_b32_e32 v56, 0x29f, v1
	v_or_b32_e32 v210, 0x2bf, v1
	v_add_u32_e32 v211, 0x2cf, v1
	v_or_b32_e32 v55, 0x32f, v1
	v_or_b32_e32 v58, 0x31f, v1
	v_or_b32_e32 v212, 0x33f, v1
	v_add_u32_e32 v213, 0x34f, v1
	v_or_b32_e32 v57, 0x3af, v1
	v_or_b32_e32 v60, 0x39f, v1
	v_or_b32_e32 v216, 0x3bf, v1
	v_add_u32_e32 v217, 0x3cf, v1
	v_or_b32_e32 v59, 0x42f, v1
	v_or_b32_e32 v62, 0x41f, v1
	v_or_b32_e32 v218, 0x43f, v1
	v_add_u32_e32 v219, 0x44f, v1
	v_or_b32_e32 v61, 0x4af, v1
	v_or_b32_e32 v64, 0x49f, v1
	v_or_b32_e32 v220, 0x4bf, v1
	v_add_u32_e32 v221, 0x4cf, v1
	v_or_b32_e32 v63, 0x52f, v1
	v_or_b32_e32 v66, 0x51f, v1
	v_or_b32_e32 v222, 0x53f, v1
	v_add_u32_e32 v223, 0x54f, v1
	v_or_b32_e32 v65, 0x5af, v1
	v_or_b32_e32 v68, 0x59f, v1
	v_or_b32_e32 v224, 0x5bf, v1
	v_add_u32_e32 v225, 0x5cf, v1
	v_or_b32_e32 v67, 0x62f, v1
	v_or_b32_e32 v70, 0x61f, v1
	v_or_b32_e32 v226, 0x63f, v1
	v_add_u32_e32 v227, 0x64f, v1
	v_or_b32_e32 v69, 0x6af, v1
	v_or_b32_e32 v72, 0x69f, v1
	v_or_b32_e32 v228, 0x6bf, v1
	v_add_u32_e32 v229, 0x6cf, v1
	v_or_b32_e32 v71, 0x72f, v1
	v_or_b32_e32 v74, 0x71f, v1
	v_or_b32_e32 v230, 0x73f, v1
	v_add_u32_e32 v231, 0x74f, v1
	v_or_b32_e32 v73, 0x7af, v1
	v_or_b32_e32 v76, 0x79f, v1
	v_or_b32_e32 v232, 0x7bf, v1
	v_add_u32_e32 v233, 0x7cf, v1
	v_lshl_or_b32 v1, v214, 3, v133
	v_cmp_lt_u32_e64 s[16:17], 2, v1
	v_cmp_lt_u32_e64 s[26:27], 10, v1
	v_cmp_lt_u32_e64 s[38:39], 18, v1
	v_writelane_b32 v253, s16, 6
	v_mov_b32_e32 v43, 0
	v_lshlrev_b32_e32 v40, 1, v139
	v_writelane_b32 v253, s17, 7
	v_cmp_lt_u32_e64 s[16:17], 4, v1
	v_mov_b32_e32 v41, v43
	v_or_b32_e32 v2, 2, v1
	v_writelane_b32 v253, s16, 8
	v_lshl_add_u64 v[44:45], s[48:49], 0, v[40:41]
	v_cmp_lt_u32_e64 s[48:49], 4, v2
	v_writelane_b32 v253, s17, 9
	v_cmp_lt_u32_e64 s[16:17], 6, v1
	s_lshr_b32 s4, s78, 8
	s_lshr_b32 s5, s69, 1
	v_writelane_b32 v253, s16, 10
	s_mul_i32 s4, s5, s4
	s_bfe_u32 s5, s78, 0x10006
	v_writelane_b32 v253, s17, 11
	v_cmp_lt_u32_e64 s[16:17], 8, v1
	s_add_i32 s4, s4, s5
	s_sub_i32 s5, 0, s69
	v_writelane_b32 v253, s16, 12
	s_mul_i32 s5, s5, s59
	s_mul_hi_u32 s5, s59, s5
	v_writelane_b32 v253, s17, 13
	v_writelane_b32 v253, s26, 14
	s_add_i32 s59, s59, s5
	s_mul_hi_u32 s5, s4, s59
	v_writelane_b32 v253, s27, 15
	v_cmp_lt_u32_e64 s[26:27], 12, v1
	s_mul_i32 s5, s5, s69
	s_sub_i32 s4, s4, s5
	v_writelane_b32 v253, s26, 16
	s_sub_i32 s5, s4, s69
	s_cmp_ge_u32 s4, s69
	v_writelane_b32 v253, s27, 17
	v_cmp_lt_u32_e64 s[26:27], 14, v1
	s_cselect_b32 s4, s5, s4
	s_sub_i32 s5, s4, s69
	v_writelane_b32 v253, s26, 18
	v_cmp_ne_u32_e64 s[6:7], 0, v1
	v_lshlrev_b32_e64 v237, v1, 1
	v_writelane_b32 v253, s27, 19
	v_cmp_lt_u32_e64 s[26:27], 16, v1
	v_lshlrev_b32_e64 v238, v1, 4
	v_lshlrev_b32_e64 v239, v1, 16
	v_writelane_b32 v253, s26, 20
	v_lshlrev_b32_e64 v240, v1, 64
	s_cmp_ge_u32 s4, s69
	v_writelane_b32 v253, s27, 21
	v_writelane_b32 v253, s38, 22
	v_mov_b32_e32 v139, v43
	v_lshlrev_b32_e32 v88, 2, v135
	v_writelane_b32 v253, s39, 23
	v_cmp_lt_u32_e64 s[38:39], 20, v1
	v_lshlrev_b32_e32 v241, 2, v242
	v_cmp_eq_u32_e64 s[74:75], 0, v242
	v_writelane_b32 v253, s38, 24
	v_lshlrev_b32_e32 v242, 5, v135
	s_cselect_b32 s60, s5, s4
	v_writelane_b32 v253, s39, 25
	v_cmp_lt_u32_e64 s[38:39], 22, v1
	v_lshrrev_b32_e32 v113, 2, v134
	v_lshlrev_b32_e32 v115, 6, v214
	v_writelane_b32 v253, s38, 26
	v_lshlrev_b32_e32 v38, 6, v134
	v_lshl_add_u64 v[78:79], s[14:15], 0, v[138:139]
	v_writelane_b32 v253, s39, 27
	v_writelane_b32 v253, s48, 28
	v_cmp_eq_u32_e64 s[38:39], 25, v1
	v_or_b32_e32 v80, 0x1000, v136
	v_writelane_b32 v253, s49, 29
	v_cmp_lt_u32_e64 s[48:49], 5, v2
	v_cmp_gt_u32_e64 s[4:5], 32, v135
	v_or_b32_e32 v84, 20, v133
	v_writelane_b32 v253, s48, 30
	v_or_b32_e32 v36, 18, v133
	v_or_b32_e32 v236, 24, v133
	v_writelane_b32 v253, s49, 31
	v_cmp_lt_u32_e64 s[48:49], 6, v2
	v_or_b32_e32 v81, 28, v133
	s_mov_b32 s15, 0
	v_writelane_b32 v253, s48, 32
	v_cmp_lt_u32_e64 s[16:17], 1, v214
	v_cmp_ne_u32_e64 s[26:27], 0, v214
	v_writelane_b32 v253, s49, 33
	v_cmp_lt_u32_e64 s[48:49], 8, v2
	v_cmp_eq_u32_e64 s[28:29], 3, v214
	v_or_b32_e32 v83, 0x101, v88
	v_writelane_b32 v253, s48, 34
	v_or_b32_e32 v90, 0x100, v88
	v_or_b32_e32 v85, 0x103, v88
	v_writelane_b32 v253, s49, 35
	v_cmp_lt_u32_e64 s[48:49], 9, v2
	v_or_b32_e32 v92, 0x102, v88
	v_or_b32_e32 v87, 0x201, v88
	v_writelane_b32 v253, s48, 36
	v_or_b32_e32 v86, 0x200, v88
	v_or_b32_e32 v89, 0x203, v88
	v_writelane_b32 v253, s49, 37
	v_cmp_lt_u32_e64 s[48:49], 10, v2
	v_or_b32_e32 v91, 0x301, v88
	v_or_b32_e32 v98, 0x300, v88
	v_writelane_b32 v253, s48, 38
	v_or_b32_e32 v93, 0x303, v88
; DI void cmp_task(const bf16_t* Z, const bf16_t* KCC, const bf16_t* VCT, bf16_t* OCMP, unsigned* selm, int b, int hk, int tg, int lane) {
;     ...
;         unsigned word = 0u;
; #pragma unroll
;         for (int mm = 0; mm < 4; ++mm) {
;             const int jm = 8 * g + 2 * mm + h; const float v = mine[mm]; int rank = 0;
; #pragma unroll
;             for (int T = 0; T < 4; ++T)
; #pragma unroll
;                 for (int m2 = 0; m2 < 4; ++m2) { const int je = 8 * T + 2 * m2;
;                     rank += (ev[T][m2] > v || (ev[T][m2] == v && je < jm)) ? 1 : 0; rank += (od[T][m2] > v || (od[T][m2] == v && je + 1 < jm)) ? 1 : 0; }
;             if (v >= 0.f && rank < 5) word |= 1u << jm;
; __global__ void __launch_bounds__(NTHR, 2) fwd_kernel(Args a) {
;     ...
;         for (int i = 0; i < nrow || ci < ncmp; ++i) {
;             if (ci < ncmp && (i >= nrow || (i % stride) == phase)) { const int task = gw + ci * NGW; ++ci;
	v_or_b32_e32 v100, 0x302, v88
	v_writelane_b32 v253, s49, 39
	v_cmp_lt_u32_e64 s[48:49], 16, v2
	v_or_b32_e32 v102, 0x400, v88
	v_or_b32_e32 v104, 0x402, v88
	v_writelane_b32 v253, s48, 40
	v_or_b32_e32 v99, 0x501, v88
	v_or_b32_e32 v106, 0x500, v88
	v_writelane_b32 v253, s49, 41
	v_cmp_lt_u32_e64 s[48:49], 12, v2
	v_or_b32_e32 v101, 0x503, v88
	v_or_b32_e32 v108, 0x502, v88
	v_writelane_b32 v253, s48, 42
	v_or_b32_e32 v103, 0x601, v88
	v_or_b32_e32 v110, 0x600, v88
	v_writelane_b32 v253, s49, 43
	v_cmp_lt_u32_e64 s[48:49], 17, v2
	v_or_b32_e32 v105, 0x603, v88
	v_or_b32_e32 v112, 0x602, v88
	v_writelane_b32 v253, s48, 44
	v_or_b32_e32 v107, 0x701, v88
	v_or_b32_e32 v114, 0x700, v88
	v_writelane_b32 v253, s49, 45
	v_cmp_lt_u32_e64 s[48:49], 13, v2
	v_or_b32_e32 v109, 0x703, v88
	v_or_b32_e32 v116, 0x702, v88
	v_writelane_b32 v253, s48, 46
	v_or_b32_e32 v243, 31, v242
	s_mov_b32 s46, 0x3e38aa3b
	v_writelane_b32 v253, s49, 47
	v_cmp_lt_u32_e64 s[48:49], 18, v2
	s_mov_b32 s61, 0xff800000
	s_mov_b32 s62, -1.0
	v_writelane_b32 v253, s48, 48
	v_lshlrev_b32_e32 v120, 2, v88
	v_mov_b32_e32 v244, 0x2200
	v_writelane_b32 v253, s49, 49
	v_cmp_lt_u32_e64 s[48:49], 14, v2
	v_mov_b32_e32 v245, 0xff800000
	s_mov_b32 s63, 0
	v_writelane_b32 v253, s48, 50
	s_mov_b32 s64, 0
	s_nop 0
	v_writelane_b32 v253, s49, 51
	v_cmp_lt_u32_e64 s[48:49], 20, v2
	s_nop 1
	v_writelane_b32 v253, s48, 52
	s_nop 1
	v_writelane_b32 v253, s49, 53
	v_cmp_lt_u32_e64 s[48:49], 21, v2
	s_nop 1
	v_writelane_b32 v253, s48, 54
	s_nop 1
	v_writelane_b32 v253, s49, 55
	v_cmp_lt_u32_e64 s[48:49], 22, v2
	s_nop 1
	v_writelane_b32 v253, s48, 56
	s_nop 1
	v_writelane_b32 v253, s49, 57
	v_cmp_lt_u32_e64 s[48:49], 24, v2
	s_nop 1
	v_writelane_b32 v253, s48, 58
	s_nop 1
	v_writelane_b32 v253, s49, 59
	v_cmp_lt_u32_e64 s[48:49], 25, v2
	v_or_b32_e32 v2, 4, v1
	s_nop 0
	v_writelane_b32 v253, s48, 60
	s_nop 1
	v_writelane_b32 v253, s49, 61
	v_cmp_lt_u32_e64 s[48:49], 5, v2
	s_nop 1
	v_writelane_b32 v253, s48, 62
	s_nop 1
	v_writelane_b32 v253, s49, 63
	v_cmp_lt_u32_e64 s[48:49], 6, v2
	s_nop 1
	v_writelane_b32 v254, s48, 0
	s_nop 1
	v_writelane_b32 v254, s49, 1
	v_cmp_lt_u32_e64 s[48:49], 8, v2
	s_nop 1
	v_writelane_b32 v254, s48, 2
	s_nop 1
	v_writelane_b32 v254, s49, 3
	v_cmp_lt_u32_e64 s[48:49], 9, v2
	s_nop 1
	v_writelane_b32 v254, s48, 4
	s_nop 1
	v_writelane_b32 v254, s49, 5
	v_cmp_lt_u32_e64 s[48:49], 10, v2
	s_nop 1
	v_writelane_b32 v254, s48, 6
	s_nop 1
	v_writelane_b32 v254, s49, 7
	v_cmp_lt_u32_e64 s[48:49], 11, v2
	s_nop 1
	v_writelane_b32 v254, s48, 8
	s_nop 1
	v_writelane_b32 v254, s49, 9
	v_cmp_lt_u32_e64 s[48:49], 12, v2
	s_nop 1
	v_writelane_b32 v254, s48, 10
	s_nop 1
	v_writelane_b32 v254, s49, 11
	v_cmp_lt_u32_e64 s[48:49], 13, v2
	s_nop 1
	v_writelane_b32 v254, s48, 12
	s_nop 1
	v_writelane_b32 v254, s49, 13
	v_cmp_lt_u32_e64 s[48:49], 14, v2
	s_nop 1
	v_writelane_b32 v254, s48, 14
	s_nop 1
	v_writelane_b32 v254, s49, 15
	v_cmp_lt_u32_e64 s[48:49], 16, v2
	s_nop 1
	v_writelane_b32 v254, s48, 16
	s_nop 1
	v_writelane_b32 v254, s49, 17
	v_cmp_lt_u32_e64 s[48:49], 17, v2
	s_nop 1
	v_writelane_b32 v254, s48, 18
	s_nop 1
	v_writelane_b32 v254, s49, 19
	v_cmp_lt_u32_e64 s[48:49], 18, v2
	s_nop 1
	v_writelane_b32 v254, s48, 20
	s_nop 1
	v_writelane_b32 v254, s49, 21
	v_cmp_lt_u32_e64 s[48:49], 19, v2
	s_nop 1
	v_writelane_b32 v254, s48, 22
	s_nop 1
	v_writelane_b32 v254, s49, 23
	v_cmp_lt_u32_e64 s[48:49], 20, v2
	s_nop 1
	v_writelane_b32 v254, s48, 24
	s_nop 1
	v_writelane_b32 v254, s49, 25
	v_cmp_lt_u32_e64 s[48:49], 21, v2
	s_nop 1
	v_writelane_b32 v254, s48, 26
	s_nop 1
	v_writelane_b32 v254, s49, 27
	v_cmp_lt_u32_e64 s[48:49], 22, v2
	s_nop 1
	v_writelane_b32 v254, s48, 28
	s_nop 1
	v_writelane_b32 v254, s49, 29
	v_cmp_lt_u32_e64 s[48:49], 24, v2
	s_nop 1
	v_writelane_b32 v254, s48, 30
	s_nop 1
	v_writelane_b32 v254, s49, 31
	v_cmp_lt_u32_e64 s[48:49], 25, v2
	s_nop 1
	v_writelane_b32 v254, s48, 32
	s_nop 1
	v_writelane_b32 v254, s49, 33
	v_cmp_lt_u32_e64 s[48:49], 26, v2
	s_nop 1
	v_writelane_b32 v254, s48, 34
	s_nop 1
	v_writelane_b32 v254, s49, 35
	v_cmp_lt_u32_e64 s[48:49], 27, v2
	v_or_b32_e32 v2, 6, v1
	v_and_b32_e32 v1, 35, v0
	v_writelane_b32 v254, s48, 36
	v_cmp_lt_u32_e64 s[70:71], 29, v2
	v_cmp_eq_u32_e64 s[72:73], 0, v1
	v_writelane_b32 v254, s49, 37
	v_cmp_lt_u32_e64 s[48:49], 8, v2
	v_mbcnt_lo_u32_b32 v1, -1, 0
	v_mbcnt_hi_u32_b32 v246, -1, v1
	v_writelane_b32 v254, s48, 38
	s_nop 1
	v_writelane_b32 v254, s49, 39
	v_cmp_lt_u32_e64 s[48:49], 9, v2
	s_nop 1
	v_writelane_b32 v254, s48, 40
	s_nop 1
	v_writelane_b32 v254, s49, 41
	v_cmp_lt_u32_e64 s[48:49], 10, v2
	s_nop 1
	v_writelane_b32 v254, s48, 42
	s_nop 1
	v_writelane_b32 v254, s49, 43
	v_cmp_lt_u32_e64 s[48:49], 11, v2
	s_nop 1
	v_writelane_b32 v254, s48, 44
	s_nop 1
	v_writelane_b32 v254, s49, 45
	v_cmp_lt_u32_e64 s[48:49], 12, v2
	s_nop 1
	v_writelane_b32 v254, s48, 46
	s_nop 1
	v_writelane_b32 v254, s49, 47
	v_cmp_lt_u32_e64 s[48:49], 13, v2
	s_nop 1
	v_writelane_b32 v254, s48, 48
	s_nop 1
	v_writelane_b32 v254, s49, 49
	v_cmp_lt_u32_e64 s[48:49], 14, v2
	s_nop 1
	v_writelane_b32 v254, s48, 50
	s_nop 1
	v_writelane_b32 v254, s49, 51
	v_cmp_lt_u32_e64 s[48:49], 16, v2
	s_nop 1
	v_writelane_b32 v254, s48, 52
	s_nop 1
	v_writelane_b32 v254, s49, 53
	v_cmp_lt_u32_e64 s[48:49], 17, v2
	s_nop 1
	v_writelane_b32 v254, s48, 54
	s_nop 1
	v_writelane_b32 v254, s49, 55
	v_cmp_lt_u32_e64 s[48:49], 18, v2
	s_nop 1
	v_writelane_b32 v254, s48, 56
	s_nop 1
	v_writelane_b32 v254, s49, 57
	v_cmp_lt_u32_e64 s[48:49], 19, v2
	s_nop 1
	v_writelane_b32 v254, s48, 58
	s_nop 1
	v_writelane_b32 v254, s49, 59
	v_cmp_lt_u32_e64 s[48:49], 20, v2
	s_nop 1
	v_writelane_b32 v254, s48, 60
	s_nop 1
	v_writelane_b32 v254, s49, 61
	v_cmp_lt_u32_e64 s[48:49], 21, v2
	s_nop 1
	v_writelane_b32 v254, s48, 62
	s_nop 1
	v_writelane_b32 v254, s49, 63
	v_cmp_lt_u32_e64 s[48:49], 22, v2
	s_nop 1
	v_writelane_b32 v255, s48, 0
	s_nop 1
	v_writelane_b32 v255, s49, 1
	v_cmp_lt_u32_e64 s[48:49], 24, v2
	s_nop 1
	v_writelane_b32 v255, s48, 2
	s_nop 1
	v_writelane_b32 v255, s49, 3
	v_cmp_lt_u32_e64 s[48:49], 25, v2
	s_nop 1
	v_writelane_b32 v255, s48, 4
	s_nop 1
	v_writelane_b32 v255, s49, 5
	v_cmp_lt_u32_e64 s[48:49], 26, v2
	s_nop 1
	v_writelane_b32 v255, s48, 6
	s_nop 1
	v_writelane_b32 v255, s49, 7
	v_cmp_lt_u32_e64 s[48:49], 27, v2
	s_nop 1
	v_writelane_b32 v255, s48, 8
	s_nop 1
	v_writelane_b32 v255, s49, 9
	v_cmp_lt_u32_e64 s[48:49], 28, v2
	v_lshlrev_b64 v[2:3], v135, -1
	v_not_b32_e32 v111, v3
	v_writelane_b32 v255, s48, 10
	v_not_b32_e32 v118, v2
	s_nop 0
	v_writelane_b32 v255, s49, 11
	s_mov_b64 s[48:49], exec
	s_mov_b64 exec, 1
	v_mov_b32_e32 v1, 0
	v_mov_b32_e32 v2, 1
	ds_add_rtn_u32 v2, v1, v2
	s_waitcnt lgkmcnt(0)
	v_readfirstlane_b32 s47, v2
	s_mov_b64 exec, s[48:49]
	s_cmpk_lt_u32 s47, 0x80
	s_cselect_b64 s[8:9], -1, 0
	s_branch .LBB0_477
